# K-loops P2/P5/P7/P11: loop counter and pointer increments plus the exit compare hoisted from behind the loop-back barrier into the last MFMA block
# baseline (speedup 1.0000x reference)
.Lsprio_p2:
.LBB0_212:
	ds_read_b128 v[128:131], v175
	ds_read_b128 v[132:135], v175 offset:1024
	ds_read_b128 v[136:139], v175 offset:2048
	ds_read_b128 v[140:143], v175 offset:3072
	ds_read_b128 v[166:169], v176
	ds_read_b128 v[182:185], v176 offset:1024
	ds_read_b128 v[186:189], v176 offset:2048
	ds_read_b128 v[190:193], v176 offset:3072
	s_add_u32 s36, s0, 0xfffc0080
	s_addc_u32 s37, s1, -1
	s_cmp_eq_u32 s45, 12
	s_cselect_b32 s39, s40, s37
	s_cselect_b32 s38, s41, s36
	s_cselect_b32 s37, s27, s44
	s_cselect_b32 s36, s42, s43
	v_lshl_add_u64 v[170:171], s[0:1], 0, v[156:157]
	s_add_i32 m0, s35, 0xc000
	ds_read_b128 v[194:197], v177
	ds_read_b128 v[198:201], v177 offset:1024
	ds_read_b128 v[202:205], v177 offset:2048
	ds_read_b128 v[210:213], v177 offset:3072
	ds_read_b128 v[214:217], v177 offset:4096
	ds_read_b128 v[218:221], v177 offset:5120
	ds_read_b128 v[222:225], v177 offset:6144
	ds_read_b128 v[226:229], v177 offset:7168
	global_load_lds_dwordx4 v[170:171], off
	v_lshl_add_u64 v[170:171], s[0:1], 0, v[158:159]
	s_add_i32 m0, s35, 0xe000
	s_nop 0
	global_load_lds_dwordx4 v[170:171], off
	s_waitcnt vmcnt(8)
	s_waitcnt lgkmcnt(0)
	s_barrier
	s_waitcnt lgkmcnt(0)
	v_mfma_f32_16x16x32_bf16 v[124:127], v[128:131], v[194:197], v[124:127]
	v_mfma_f32_16x16x32_bf16 v[120:123], v[136:139], v[194:197], v[120:123]
	v_mfma_f32_16x16x32_bf16 v[112:115], v[128:131], v[202:205], v[112:115]
	v_mfma_f32_16x16x32_bf16 v[104:107], v[136:139], v[202:205], v[104:107]
	v_mfma_f32_16x16x32_bf16 v[96:99], v[128:131], v[214:217], v[96:99]
	v_mfma_f32_16x16x32_bf16 v[88:91], v[136:139], v[214:217], v[88:91]
	v_mfma_f32_16x16x32_bf16 v[80:83], v[128:131], v[222:225], v[80:83]
	v_mfma_f32_16x16x32_bf16 v[72:75], v[136:139], v[222:225], v[72:75]
	v_mfma_f32_16x16x32_bf16 v[124:127], v[132:135], v[198:201], v[124:127]
	v_mfma_f32_16x16x32_bf16 v[120:123], v[140:143], v[198:201], v[120:123]
	v_mfma_f32_16x16x32_bf16 v[112:115], v[132:135], v[210:213], v[112:115]
	v_mfma_f32_16x16x32_bf16 v[104:107], v[140:143], v[210:213], v[104:107]
	v_mfma_f32_16x16x32_bf16 v[96:99], v[132:135], v[218:221], v[96:99]
	v_mfma_f32_16x16x32_bf16 v[88:91], v[140:143], v[218:221], v[88:91]
	v_mfma_f32_16x16x32_bf16 v[80:83], v[132:135], v[226:229], v[80:83]
	v_mfma_f32_16x16x32_bf16 v[72:75], v[140:143], v[226:229], v[72:75]
	v_mfma_f32_16x16x32_bf16 v[116:119], v[166:169], v[194:197], v[116:119]
	v_mfma_f32_16x16x32_bf16 v[108:111], v[186:189], v[194:197], v[108:111]
	v_mfma_f32_16x16x32_bf16 v[100:103], v[166:169], v[202:205], v[100:103]
	v_mfma_f32_16x16x32_bf16 v[92:95], v[186:189], v[202:205], v[92:95]
	v_mfma_f32_16x16x32_bf16 v[84:87], v[166:169], v[214:217], v[84:87]
	v_mfma_f32_16x16x32_bf16 v[76:79], v[186:189], v[214:217], v[76:79]
	v_mfma_f32_16x16x32_bf16 v[68:71], v[166:169], v[222:225], v[68:71]
	v_mfma_f32_16x16x32_bf16 v[64:67], v[186:189], v[222:225], v[64:67]
	v_mfma_f32_16x16x32_bf16 v[116:119], v[182:185], v[198:201], v[116:119]
	v_mfma_f32_16x16x32_bf16 v[108:111], v[190:193], v[198:201], v[108:111]
	v_mfma_f32_16x16x32_bf16 v[100:103], v[182:185], v[210:213], v[100:103]
	v_mfma_f32_16x16x32_bf16 v[92:95], v[190:193], v[210:213], v[92:95]
	v_mfma_f32_16x16x32_bf16 v[84:87], v[182:185], v[218:221], v[84:87]
	v_mfma_f32_16x16x32_bf16 v[76:79], v[190:193], v[218:221], v[76:79]
	v_mfma_f32_16x16x32_bf16 v[68:71], v[182:185], v[226:229], v[68:71]
	v_mfma_f32_16x16x32_bf16 v[64:67], v[190:193], v[226:229], v[64:67]
	s_barrier
	s_add_i32 s73, s64, s3
	v_lshl_add_u64 v[170:171], s[36:37], 0, v[146:147]
	s_mov_b32 m0, s73
	ds_read_b128 v[194:197], v177 offset:16384
	ds_read_b128 v[198:201], v177 offset:17408
	ds_read_b128 v[202:205], v177 offset:18432
	ds_read_b128 v[210:213], v177 offset:19456
	ds_read_b128 v[214:217], v177 offset:20480
	ds_read_b128 v[218:221], v177 offset:21504
	ds_read_b128 v[222:225], v177 offset:22528
	ds_read_b128 v[226:229], v177 offset:23552
	global_load_lds_dwordx4 v[170:171], off
	s_add_i32 m0, s73, 0x2000
	s_add_u32 s74, s36, 0x40000
	v_lshl_add_u64 v[206:207], s[36:37], 0, v[150:151]
	s_addc_u32 s75, s37, 0
	s_add_i32 s73, s65, s3
	global_load_lds_dwordx4 v[206:207], off
	v_lshl_add_u64 v[230:231], s[74:75], 0, v[146:147]
	s_mov_b32 m0, s73
	v_lshl_add_u64 v[232:233], s[38:39], 0, v[148:149]
	global_load_lds_dwordx4 v[230:231], off
	v_lshl_add_u64 v[230:231], s[74:75], 0, v[150:151]
	s_add_i32 m0, s73, 0x2000
	s_nop 0
	global_load_lds_dwordx4 v[230:231], off
	v_lshl_add_u64 v[230:231], s[38:39], 0, v[144:145]
	s_mov_b32 m0, s35
	s_nop 0
	global_load_lds_dwordx4 v[230:231], off
	s_mov_b32 m0, s46
	s_nop 0
	global_load_lds_dwordx4 v[232:233], off
	s_waitcnt vmcnt(8)
	s_waitcnt lgkmcnt(0)
	s_barrier
	s_waitcnt lgkmcnt(0)
	v_mfma_f32_16x16x32_bf16 v[60:63], v[128:131], v[194:197], v[60:63]
	v_mfma_f32_16x16x32_bf16 v[56:59], v[136:139], v[194:197], v[56:59]
	v_mfma_f32_16x16x32_bf16 v[48:51], v[128:131], v[202:205], v[48:51]
	v_mfma_f32_16x16x32_bf16 v[44:47], v[136:139], v[202:205], v[44:47]
	v_mfma_f32_16x16x32_bf16 v[32:35], v[128:131], v[214:217], v[32:35]
	v_mfma_f32_16x16x32_bf16 v[28:31], v[136:139], v[214:217], v[28:31]
	v_mfma_f32_16x16x32_bf16 v[16:19], v[128:131], v[222:225], v[16:19]
	v_mfma_f32_16x16x32_bf16 v[12:15], v[136:139], v[222:225], v[12:15]
	v_mfma_f32_16x16x32_bf16 v[60:63], v[132:135], v[198:201], v[60:63]
	v_mfma_f32_16x16x32_bf16 v[56:59], v[140:143], v[198:201], v[56:59]
	v_mfma_f32_16x16x32_bf16 v[48:51], v[132:135], v[210:213], v[48:51]
	v_mfma_f32_16x16x32_bf16 v[44:47], v[140:143], v[210:213], v[44:47]
	v_mfma_f32_16x16x32_bf16 v[32:35], v[132:135], v[218:221], v[32:35]
	v_mfma_f32_16x16x32_bf16 v[28:31], v[140:143], v[218:221], v[28:31]
	v_mfma_f32_16x16x32_bf16 v[16:19], v[132:135], v[226:229], v[16:19]
	v_mfma_f32_16x16x32_bf16 v[12:15], v[140:143], v[226:229], v[12:15]
	v_mfma_f32_16x16x32_bf16 v[52:55], v[166:169], v[194:197], v[52:55]
	v_mfma_f32_16x16x32_bf16 v[40:43], v[186:189], v[194:197], v[40:43]
	v_mfma_f32_16x16x32_bf16 v[36:39], v[166:169], v[202:205], v[36:39]
	v_mfma_f32_16x16x32_bf16 v[24:27], v[186:189], v[202:205], v[24:27]
	v_mfma_f32_16x16x32_bf16 v[20:23], v[166:169], v[214:217], v[20:23]
	v_mfma_f32_16x16x32_bf16 v[8:11], v[186:189], v[214:217], v[8:11]
	v_mfma_f32_16x16x32_bf16 v[4:7], v[166:169], v[222:225], v[4:7]
	v_mfma_f32_16x16x32_bf16 v[0:3], v[186:189], v[222:225], v[0:3]
	v_mfma_f32_16x16x32_bf16 v[52:55], v[182:185], v[198:201], v[52:55]
	v_mfma_f32_16x16x32_bf16 v[40:43], v[190:193], v[198:201], v[40:43]
	v_mfma_f32_16x16x32_bf16 v[36:39], v[182:185], v[210:213], v[36:39]
	v_mfma_f32_16x16x32_bf16 v[24:27], v[190:193], v[210:213], v[24:27]
	v_mfma_f32_16x16x32_bf16 v[20:23], v[182:185], v[218:221], v[20:23]
	v_mfma_f32_16x16x32_bf16 v[8:11], v[190:193], v[218:221], v[8:11]
	v_mfma_f32_16x16x32_bf16 v[4:7], v[182:185], v[226:229], v[4:7]
	v_mfma_f32_16x16x32_bf16 v[0:3], v[190:193], v[226:229], v[0:3]
	s_barrier
	s_add_i32 s73, 0, 0x18000
	s_add_i32 s74, 0, 0x1c000
	v_add_u32_e32 v140, s73, v173
	v_add_u32_e32 v152, s74, v173
	ds_read_b128 v[128:131], v140
	ds_read_b128 v[132:135], v140 offset:1024
	ds_read_b128 v[136:139], v140 offset:2048
	ds_read_b128 v[140:143], v140 offset:3072
	ds_read_b128 v[166:169], v152
	ds_read_b128 v[182:185], v152 offset:1024
	ds_read_b128 v[186:189], v152 offset:2048
	ds_read_b128 v[190:193], v152 offset:3072
	s_add_u32 s38, s38, 0x40000
	s_addc_u32 s39, s39, 0
	s_mov_b32 m0, s47
	v_lshl_add_u64 v[234:235], s[38:39], 0, v[144:145]
	ds_read_b128 v[194:197], v177 offset:32768
	ds_read_b128 v[198:201], v177 offset:33792
	ds_read_b128 v[202:205], v177 offset:34816
	ds_read_b128 v[210:213], v177 offset:35840
	ds_read_b128 v[214:217], v177 offset:36864
	ds_read_b128 v[218:221], v177 offset:37888
	ds_read_b128 v[222:225], v177 offset:38912
	ds_read_b128 v[226:229], v177 offset:39936
	global_load_lds_dwordx4 v[234:235], off
	v_lshl_add_u64 v[234:235], s[38:39], 0, v[148:149]
	s_mov_b32 m0, s48
	s_nop 0
	global_load_lds_dwordx4 v[234:235], off
	s_waitcnt vmcnt(8)
	s_waitcnt lgkmcnt(0)
	s_barrier
	s_waitcnt lgkmcnt(0)
	v_mfma_f32_16x16x32_bf16 v[124:127], v[128:131], v[194:197], v[124:127]
	v_mfma_f32_16x16x32_bf16 v[120:123], v[136:139], v[194:197], v[120:123]
	v_mfma_f32_16x16x32_bf16 v[112:115], v[128:131], v[202:205], v[112:115]
	v_mfma_f32_16x16x32_bf16 v[104:107], v[136:139], v[202:205], v[104:107]
	v_mfma_f32_16x16x32_bf16 v[96:99], v[128:131], v[214:217], v[96:99]
	v_mfma_f32_16x16x32_bf16 v[88:91], v[136:139], v[214:217], v[88:91]
	v_mfma_f32_16x16x32_bf16 v[80:83], v[128:131], v[222:225], v[80:83]
	v_mfma_f32_16x16x32_bf16 v[72:75], v[136:139], v[222:225], v[72:75]
	v_mfma_f32_16x16x32_bf16 v[124:127], v[132:135], v[198:201], v[124:127]
	v_mfma_f32_16x16x32_bf16 v[120:123], v[140:143], v[198:201], v[120:123]
	v_mfma_f32_16x16x32_bf16 v[112:115], v[132:135], v[210:213], v[112:115]
	v_mfma_f32_16x16x32_bf16 v[104:107], v[140:143], v[210:213], v[104:107]
	v_mfma_f32_16x16x32_bf16 v[96:99], v[132:135], v[218:221], v[96:99]
	v_mfma_f32_16x16x32_bf16 v[88:91], v[140:143], v[218:221], v[88:91]
	v_mfma_f32_16x16x32_bf16 v[80:83], v[132:135], v[226:229], v[80:83]
	v_mfma_f32_16x16x32_bf16 v[72:75], v[140:143], v[226:229], v[72:75]
	v_mfma_f32_16x16x32_bf16 v[116:119], v[166:169], v[194:197], v[116:119]
	v_mfma_f32_16x16x32_bf16 v[108:111], v[186:189], v[194:197], v[108:111]
	v_mfma_f32_16x16x32_bf16 v[100:103], v[166:169], v[202:205], v[100:103]
	v_mfma_f32_16x16x32_bf16 v[92:95], v[186:189], v[202:205], v[92:95]
	v_mfma_f32_16x16x32_bf16 v[84:87], v[166:169], v[214:217], v[84:87]
	v_mfma_f32_16x16x32_bf16 v[76:79], v[186:189], v[214:217], v[76:79]
	v_mfma_f32_16x16x32_bf16 v[68:71], v[166:169], v[222:225], v[68:71]
	v_mfma_f32_16x16x32_bf16 v[64:67], v[186:189], v[222:225], v[64:67]
	v_mfma_f32_16x16x32_bf16 v[116:119], v[182:185], v[198:201], v[116:119]
	v_mfma_f32_16x16x32_bf16 v[108:111], v[190:193], v[198:201], v[108:111]
	v_mfma_f32_16x16x32_bf16 v[100:103], v[182:185], v[210:213], v[100:103]
	v_mfma_f32_16x16x32_bf16 v[92:95], v[190:193], v[210:213], v[92:95]
	v_mfma_f32_16x16x32_bf16 v[84:87], v[182:185], v[218:221], v[84:87]
	v_mfma_f32_16x16x32_bf16 v[76:79], v[190:193], v[218:221], v[76:79]
	v_mfma_f32_16x16x32_bf16 v[68:71], v[182:185], v[226:229], v[68:71]
	v_mfma_f32_16x16x32_bf16 v[64:67], v[190:193], v[226:229], v[64:67]
	s_barrier
	s_add_i32 s38, s73, s3
	v_lshl_add_u64 v[170:171], v[170:171], 0, s[18:19]
	s_mov_b32 m0, s38
	ds_read_b128 v[194:197], v177 offset:49152
	ds_read_b128 v[198:201], v177 offset:50176
	ds_read_b128 v[202:205], v177 offset:51200
	ds_read_b128 v[210:213], v177 offset:52224
	ds_read_b128 v[214:217], v177 offset:53248
	ds_read_b128 v[218:221], v177 offset:54272
	ds_read_b128 v[222:225], v177 offset:55296
	ds_read_b128 v[226:229], v177 offset:56320
	global_load_lds_dwordx4 v[170:171], off
	s_add_i32 m0, s38, 0x2000
	s_add_u32 s36, s36, 0x40080
	v_lshl_add_u64 v[170:171], v[206:207], 0, s[18:19]
	s_addc_u32 s37, s37, 0
	s_add_i32 s38, s74, s3
	global_load_lds_dwordx4 v[170:171], off
	v_lshl_add_u64 v[170:171], s[36:37], 0, v[146:147]
	s_mov_b32 m0, s38
	s_nop 0
	global_load_lds_dwordx4 v[170:171], off
	v_lshl_add_u64 v[170:171], s[36:37], 0, v[150:151]
	s_add_i32 m0, s38, 0x2000
	s_nop 0
	global_load_lds_dwordx4 v[170:171], off
	v_lshl_add_u64 v[170:171], v[230:231], 0, s[18:19]
	s_mov_b32 m0, s50
	s_nop 0
	global_load_lds_dwordx4 v[170:171], off
	v_lshl_add_u64 v[170:171], v[232:233], 0, s[18:19]
	s_mov_b32 m0, s51
	s_nop 0
	global_load_lds_dwordx4 v[170:171], off
	s_waitcnt vmcnt(8)
	s_waitcnt lgkmcnt(0)
	s_barrier
	s_waitcnt lgkmcnt(0)
	v_mfma_f32_16x16x32_bf16 v[60:63], v[128:131], v[194:197], v[60:63]
	v_mfma_f32_16x16x32_bf16 v[56:59], v[136:139], v[194:197], v[56:59]
	v_mfma_f32_16x16x32_bf16 v[48:51], v[128:131], v[202:205], v[48:51]
	v_mfma_f32_16x16x32_bf16 v[44:47], v[136:139], v[202:205], v[44:47]
	v_mfma_f32_16x16x32_bf16 v[32:35], v[128:131], v[214:217], v[32:35]
	v_mfma_f32_16x16x32_bf16 v[28:31], v[136:139], v[214:217], v[28:31]
	v_mfma_f32_16x16x32_bf16 v[16:19], v[128:131], v[222:225], v[16:19]
	v_mfma_f32_16x16x32_bf16 v[12:15], v[136:139], v[222:225], v[12:15]
	v_mfma_f32_16x16x32_bf16 v[60:63], v[132:135], v[198:201], v[60:63]
	s_add_i32 s45, s45, 2
	s_add_u32 s0, s0, 0x100
	s_addc_u32 s1, s1, 0
	s_add_u32 s43, s43, 0x100
	s_addc_u32 s44, s44, 0
	s_cmp_gt_u32 s45, 13
	v_mfma_f32_16x16x32_bf16 v[56:59], v[140:143], v[198:201], v[56:59]
	v_mfma_f32_16x16x32_bf16 v[48:51], v[132:135], v[210:213], v[48:51]
	v_mfma_f32_16x16x32_bf16 v[44:47], v[140:143], v[210:213], v[44:47]
	v_mfma_f32_16x16x32_bf16 v[32:35], v[132:135], v[218:221], v[32:35]
	v_mfma_f32_16x16x32_bf16 v[28:31], v[140:143], v[218:221], v[28:31]
	v_mfma_f32_16x16x32_bf16 v[16:19], v[132:135], v[226:229], v[16:19]
	v_mfma_f32_16x16x32_bf16 v[12:15], v[140:143], v[226:229], v[12:15]
	v_mfma_f32_16x16x32_bf16 v[52:55], v[166:169], v[194:197], v[52:55]
	v_mfma_f32_16x16x32_bf16 v[40:43], v[186:189], v[194:197], v[40:43]
	v_mfma_f32_16x16x32_bf16 v[36:39], v[166:169], v[202:205], v[36:39]
	v_mfma_f32_16x16x32_bf16 v[24:27], v[186:189], v[202:205], v[24:27]
	v_mfma_f32_16x16x32_bf16 v[20:23], v[166:169], v[214:217], v[20:23]
	v_mfma_f32_16x16x32_bf16 v[8:11], v[186:189], v[214:217], v[8:11]
	v_mfma_f32_16x16x32_bf16 v[4:7], v[166:169], v[222:225], v[4:7]
	v_mfma_f32_16x16x32_bf16 v[0:3], v[186:189], v[222:225], v[0:3]
	v_mfma_f32_16x16x32_bf16 v[52:55], v[182:185], v[198:201], v[52:55]
	v_mfma_f32_16x16x32_bf16 v[40:43], v[190:193], v[198:201], v[40:43]
	v_mfma_f32_16x16x32_bf16 v[36:39], v[182:185], v[210:213], v[36:39]
	v_mfma_f32_16x16x32_bf16 v[24:27], v[190:193], v[210:213], v[24:27]
	v_mfma_f32_16x16x32_bf16 v[20:23], v[182:185], v[218:221], v[20:23]
	v_mfma_f32_16x16x32_bf16 v[8:11], v[190:193], v[218:221], v[8:11]
	v_mfma_f32_16x16x32_bf16 v[4:7], v[182:185], v[226:229], v[4:7]
	v_mfma_f32_16x16x32_bf16 v[0:3], v[190:193], v[226:229], v[0:3]
	s_barrier
	s_cbranch_scc0 .LBB0_212
	s_setprio 0
	s_and_b64 vcc, exec, s[20:21]
	s_cbranch_vccz .LBB0_215
	s_barrier

.Lsprio_p5:
.LBB0_586:
	ds_read_b128 v[144:147], v175
	ds_read_b128 v[148:151], v175 offset:1024
	ds_read_b128 v[152:155], v175 offset:2048
	ds_read_b128 v[156:159], v175 offset:3072
	ds_read_b128 v[160:163], v176
	ds_read_b128 v[164:167], v176 offset:1024
	ds_read_b128 v[168:171], v176 offset:2048
	ds_read_b128 v[180:183], v176 offset:3072
	s_add_u32 s28, s26, 0xfffc0080
	s_addc_u32 s29, s27, -1
	s_cmp_eq_u32 s63, 12
	s_cselect_b32 s31, s25, s29
	s_cselect_b32 s30, s51, s28
	s_cselect_b32 s29, s19, s62
	s_cselect_b32 s28, s54, s55
	v_lshl_add_u64 v[218:219], s[26:27], 0, v[136:137]
	s_add_i32 m0, s34, 0xc000
	ds_read_b128 v[184:187], v177
	ds_read_b128 v[188:191], v177 offset:1024
	ds_read_b128 v[192:195], v177 offset:2048
	ds_read_b128 v[196:199], v177 offset:3072
	ds_read_b128 v[200:203], v177 offset:4096
	ds_read_b128 v[204:207], v177 offset:5120
	ds_read_b128 v[210:213], v177 offset:6144
	ds_read_b128 v[214:217], v177 offset:7168
	global_load_lds_dwordx4 v[218:219], off
	v_lshl_add_u64 v[218:219], s[26:27], 0, v[138:139]
	s_add_i32 m0, s34, 0xe000
	s_nop 0
	global_load_lds_dwordx4 v[218:219], off
	s_waitcnt vmcnt(8)
	s_waitcnt lgkmcnt(0)
	s_barrier
	s_waitcnt lgkmcnt(0)
	v_mfma_f32_16x16x32_bf16 v[124:127], v[144:147], v[184:187], v[124:127]
	v_mfma_f32_16x16x32_bf16 v[120:123], v[152:155], v[184:187], v[120:123]
	v_mfma_f32_16x16x32_bf16 v[108:111], v[144:147], v[192:195], v[108:111]
	v_mfma_f32_16x16x32_bf16 v[104:107], v[152:155], v[192:195], v[104:107]
	v_mfma_f32_16x16x32_bf16 v[92:95], v[144:147], v[200:203], v[92:95]
	v_mfma_f32_16x16x32_bf16 v[88:91], v[152:155], v[200:203], v[88:91]
	v_mfma_f32_16x16x32_bf16 v[76:79], v[144:147], v[210:213], v[76:79]
	v_mfma_f32_16x16x32_bf16 v[72:75], v[152:155], v[210:213], v[72:75]
	v_mfma_f32_16x16x32_bf16 v[124:127], v[148:151], v[188:191], v[124:127]
	v_mfma_f32_16x16x32_bf16 v[120:123], v[156:159], v[188:191], v[120:123]
	v_mfma_f32_16x16x32_bf16 v[108:111], v[148:151], v[196:199], v[108:111]
	v_mfma_f32_16x16x32_bf16 v[104:107], v[156:159], v[196:199], v[104:107]
	v_mfma_f32_16x16x32_bf16 v[92:95], v[148:151], v[204:207], v[92:95]
	v_mfma_f32_16x16x32_bf16 v[88:91], v[156:159], v[204:207], v[88:91]
	v_mfma_f32_16x16x32_bf16 v[76:79], v[148:151], v[214:217], v[76:79]
	v_mfma_f32_16x16x32_bf16 v[72:75], v[156:159], v[214:217], v[72:75]
	v_mfma_f32_16x16x32_bf16 v[116:119], v[160:163], v[184:187], v[116:119]
	v_mfma_f32_16x16x32_bf16 v[112:115], v[168:171], v[184:187], v[112:115]
	v_mfma_f32_16x16x32_bf16 v[100:103], v[160:163], v[192:195], v[100:103]
	v_mfma_f32_16x16x32_bf16 v[96:99], v[168:171], v[192:195], v[96:99]
	v_mfma_f32_16x16x32_bf16 v[84:87], v[160:163], v[200:203], v[84:87]
	v_mfma_f32_16x16x32_bf16 v[80:83], v[168:171], v[200:203], v[80:83]
	v_mfma_f32_16x16x32_bf16 v[68:71], v[160:163], v[210:213], v[68:71]
	v_mfma_f32_16x16x32_bf16 v[64:67], v[168:171], v[210:213], v[64:67]
	v_mfma_f32_16x16x32_bf16 v[116:119], v[164:167], v[188:191], v[116:119]
	v_mfma_f32_16x16x32_bf16 v[112:115], v[180:183], v[188:191], v[112:115]
	v_mfma_f32_16x16x32_bf16 v[100:103], v[164:167], v[196:199], v[100:103]
	v_mfma_f32_16x16x32_bf16 v[96:99], v[180:183], v[196:199], v[96:99]
	v_mfma_f32_16x16x32_bf16 v[84:87], v[164:167], v[204:207], v[84:87]
	v_mfma_f32_16x16x32_bf16 v[80:83], v[180:183], v[204:207], v[80:83]
	v_mfma_f32_16x16x32_bf16 v[68:71], v[164:167], v[214:217], v[68:71]
	v_mfma_f32_16x16x32_bf16 v[64:67], v[180:183], v[214:217], v[64:67]
	s_barrier
	s_add_i32 s64, s47, s3
	v_lshl_add_u64 v[218:219], s[28:29], 0, v[130:131]
	s_mov_b32 m0, s64
	ds_read_b128 v[184:187], v177 offset:16384
	ds_read_b128 v[188:191], v177 offset:17408
	ds_read_b128 v[192:195], v177 offset:18432
	ds_read_b128 v[196:199], v177 offset:19456
	ds_read_b128 v[200:203], v177 offset:20480
	ds_read_b128 v[204:207], v177 offset:21504
	ds_read_b128 v[210:213], v177 offset:22528
	ds_read_b128 v[214:217], v177 offset:23552
	global_load_lds_dwordx4 v[218:219], off
	s_add_i32 m0, s64, 0x2000
	s_add_u32 s64, s28, 0x40000
	v_lshl_add_u64 v[220:221], s[28:29], 0, v[134:135]
	s_addc_u32 s65, s29, 0
	s_add_i32 s66, s48, s3
	global_load_lds_dwordx4 v[220:221], off
	v_lshl_add_u64 v[222:223], s[64:65], 0, v[130:131]
	s_mov_b32 m0, s66
	v_lshl_add_u64 v[224:225], s[30:31], 0, v[132:133]
	global_load_lds_dwordx4 v[222:223], off
	v_lshl_add_u64 v[222:223], s[64:65], 0, v[134:135]
	s_add_i32 m0, s66, 0x2000
	s_nop 0
	global_load_lds_dwordx4 v[222:223], off
	v_lshl_add_u64 v[222:223], s[30:31], 0, v[128:129]
	s_mov_b32 m0, s34
	s_nop 0
	global_load_lds_dwordx4 v[222:223], off
	s_mov_b32 m0, s35
	s_nop 0
	global_load_lds_dwordx4 v[224:225], off
	s_waitcnt vmcnt(8)
	s_waitcnt lgkmcnt(0)
	s_barrier
	s_waitcnt lgkmcnt(0)
	v_mfma_f32_16x16x32_bf16 v[60:63], v[144:147], v[184:187], v[60:63]
	v_mfma_f32_16x16x32_bf16 v[56:59], v[152:155], v[184:187], v[56:59]
	v_mfma_f32_16x16x32_bf16 v[44:47], v[144:147], v[192:195], v[44:47]
	v_mfma_f32_16x16x32_bf16 v[40:43], v[152:155], v[192:195], v[40:43]
	v_mfma_f32_16x16x32_bf16 v[28:31], v[144:147], v[200:203], v[28:31]
	v_mfma_f32_16x16x32_bf16 v[24:27], v[152:155], v[200:203], v[24:27]
	v_mfma_f32_16x16x32_bf16 v[12:15], v[144:147], v[210:213], v[12:15]
	v_mfma_f32_16x16x32_bf16 v[8:11], v[152:155], v[210:213], v[8:11]
	v_mfma_f32_16x16x32_bf16 v[60:63], v[148:151], v[188:191], v[60:63]
	v_mfma_f32_16x16x32_bf16 v[56:59], v[156:159], v[188:191], v[56:59]
	v_mfma_f32_16x16x32_bf16 v[44:47], v[148:151], v[196:199], v[44:47]
	v_mfma_f32_16x16x32_bf16 v[40:43], v[156:159], v[196:199], v[40:43]
	v_mfma_f32_16x16x32_bf16 v[28:31], v[148:151], v[204:207], v[28:31]
	v_mfma_f32_16x16x32_bf16 v[24:27], v[156:159], v[204:207], v[24:27]
	v_mfma_f32_16x16x32_bf16 v[12:15], v[148:151], v[214:217], v[12:15]
	v_mfma_f32_16x16x32_bf16 v[8:11], v[156:159], v[214:217], v[8:11]
	v_mfma_f32_16x16x32_bf16 v[52:55], v[160:163], v[184:187], v[52:55]
	v_mfma_f32_16x16x32_bf16 v[48:51], v[168:171], v[184:187], v[48:51]
	v_mfma_f32_16x16x32_bf16 v[36:39], v[160:163], v[192:195], v[36:39]
	v_mfma_f32_16x16x32_bf16 v[32:35], v[168:171], v[192:195], v[32:35]
	v_mfma_f32_16x16x32_bf16 v[20:23], v[160:163], v[200:203], v[20:23]
	v_mfma_f32_16x16x32_bf16 v[16:19], v[168:171], v[200:203], v[16:19]
	v_mfma_f32_16x16x32_bf16 v[4:7], v[160:163], v[210:213], v[4:7]
	v_mfma_f32_16x16x32_bf16 v[0:3], v[168:171], v[210:213], v[0:3]
	v_mfma_f32_16x16x32_bf16 v[52:55], v[164:167], v[188:191], v[52:55]
	v_mfma_f32_16x16x32_bf16 v[48:51], v[180:183], v[188:191], v[48:51]
	v_mfma_f32_16x16x32_bf16 v[36:39], v[164:167], v[196:199], v[36:39]
	v_mfma_f32_16x16x32_bf16 v[32:35], v[180:183], v[196:199], v[32:35]
	v_mfma_f32_16x16x32_bf16 v[20:23], v[164:167], v[204:207], v[20:23]
	v_mfma_f32_16x16x32_bf16 v[16:19], v[180:183], v[204:207], v[16:19]
	v_mfma_f32_16x16x32_bf16 v[4:7], v[164:167], v[214:217], v[4:7]
	v_mfma_f32_16x16x32_bf16 v[0:3], v[180:183], v[214:217], v[0:3]
	s_barrier
	s_add_i32 s64, 0, 0x18000
	s_add_i32 s65, 0, 0x1c000
	v_add_u32_e32 v156, s64, v173
	v_add_u32_e32 v179, s65, v173
	ds_read_b128 v[144:147], v156
	ds_read_b128 v[148:151], v156 offset:1024
	ds_read_b128 v[152:155], v156 offset:2048
	ds_read_b128 v[156:159], v156 offset:3072
	ds_read_b128 v[160:163], v179
	ds_read_b128 v[164:167], v179 offset:1024
	ds_read_b128 v[168:171], v179 offset:2048
	ds_read_b128 v[180:183], v179 offset:3072
	s_add_u32 s30, s30, 0x40000
	s_addc_u32 s31, s31, 0
	s_mov_b32 m0, s36
	v_lshl_add_u64 v[226:227], s[30:31], 0, v[128:129]
	ds_read_b128 v[184:187], v177 offset:32768
	ds_read_b128 v[188:191], v177 offset:33792
	ds_read_b128 v[192:195], v177 offset:34816
	ds_read_b128 v[196:199], v177 offset:35840
	ds_read_b128 v[200:203], v177 offset:36864
	ds_read_b128 v[204:207], v177 offset:37888
	ds_read_b128 v[210:213], v177 offset:38912
	ds_read_b128 v[214:217], v177 offset:39936
	global_load_lds_dwordx4 v[226:227], off
	v_lshl_add_u64 v[226:227], s[30:31], 0, v[132:133]
	s_mov_b32 m0, s37
	s_nop 0
	global_load_lds_dwordx4 v[226:227], off
	s_waitcnt vmcnt(8)
	s_waitcnt lgkmcnt(0)
	s_barrier
	s_waitcnt lgkmcnt(0)
	v_mfma_f32_16x16x32_bf16 v[124:127], v[144:147], v[184:187], v[124:127]
	v_mfma_f32_16x16x32_bf16 v[120:123], v[152:155], v[184:187], v[120:123]
	v_mfma_f32_16x16x32_bf16 v[108:111], v[144:147], v[192:195], v[108:111]
	v_mfma_f32_16x16x32_bf16 v[104:107], v[152:155], v[192:195], v[104:107]
	v_mfma_f32_16x16x32_bf16 v[92:95], v[144:147], v[200:203], v[92:95]
	v_mfma_f32_16x16x32_bf16 v[88:91], v[152:155], v[200:203], v[88:91]
	v_mfma_f32_16x16x32_bf16 v[76:79], v[144:147], v[210:213], v[76:79]
	v_mfma_f32_16x16x32_bf16 v[72:75], v[152:155], v[210:213], v[72:75]
	v_mfma_f32_16x16x32_bf16 v[124:127], v[148:151], v[188:191], v[124:127]
	v_mfma_f32_16x16x32_bf16 v[120:123], v[156:159], v[188:191], v[120:123]
	v_mfma_f32_16x16x32_bf16 v[108:111], v[148:151], v[196:199], v[108:111]
	v_mfma_f32_16x16x32_bf16 v[104:107], v[156:159], v[196:199], v[104:107]
	v_mfma_f32_16x16x32_bf16 v[92:95], v[148:151], v[204:207], v[92:95]
	v_mfma_f32_16x16x32_bf16 v[88:91], v[156:159], v[204:207], v[88:91]
	v_mfma_f32_16x16x32_bf16 v[76:79], v[148:151], v[214:217], v[76:79]
	v_mfma_f32_16x16x32_bf16 v[72:75], v[156:159], v[214:217], v[72:75]
	v_mfma_f32_16x16x32_bf16 v[116:119], v[160:163], v[184:187], v[116:119]
	v_mfma_f32_16x16x32_bf16 v[112:115], v[168:171], v[184:187], v[112:115]
	v_mfma_f32_16x16x32_bf16 v[100:103], v[160:163], v[192:195], v[100:103]
	v_mfma_f32_16x16x32_bf16 v[96:99], v[168:171], v[192:195], v[96:99]
	v_mfma_f32_16x16x32_bf16 v[84:87], v[160:163], v[200:203], v[84:87]
	v_mfma_f32_16x16x32_bf16 v[80:83], v[168:171], v[200:203], v[80:83]
	v_mfma_f32_16x16x32_bf16 v[68:71], v[160:163], v[210:213], v[68:71]
	v_mfma_f32_16x16x32_bf16 v[64:67], v[168:171], v[210:213], v[64:67]
	v_mfma_f32_16x16x32_bf16 v[116:119], v[164:167], v[188:191], v[116:119]
	v_mfma_f32_16x16x32_bf16 v[112:115], v[180:183], v[188:191], v[112:115]
	v_mfma_f32_16x16x32_bf16 v[100:103], v[164:167], v[196:199], v[100:103]
	v_mfma_f32_16x16x32_bf16 v[96:99], v[180:183], v[196:199], v[96:99]
	v_mfma_f32_16x16x32_bf16 v[84:87], v[164:167], v[204:207], v[84:87]
	v_mfma_f32_16x16x32_bf16 v[80:83], v[180:183], v[204:207], v[80:83]
	v_mfma_f32_16x16x32_bf16 v[68:71], v[164:167], v[214:217], v[68:71]
	v_mfma_f32_16x16x32_bf16 v[64:67], v[180:183], v[214:217], v[64:67]
	s_barrier
	s_add_i32 s30, s64, s3
	v_lshl_add_u64 v[218:219], v[218:219], 0, s[12:13]
	s_mov_b32 m0, s30
	ds_read_b128 v[184:187], v177 offset:49152
	ds_read_b128 v[188:191], v177 offset:50176
	ds_read_b128 v[192:195], v177 offset:51200
	ds_read_b128 v[196:199], v177 offset:52224
	ds_read_b128 v[200:203], v177 offset:53248
	ds_read_b128 v[204:207], v177 offset:54272
	ds_read_b128 v[210:213], v177 offset:55296
	ds_read_b128 v[214:217], v177 offset:56320
	global_load_lds_dwordx4 v[218:219], off
	s_add_i32 m0, s30, 0x2000
	s_add_u32 s28, s28, 0x40080
	v_lshl_add_u64 v[218:219], v[220:221], 0, s[12:13]
	s_addc_u32 s29, s29, 0
	s_add_i32 s30, s65, s3
	global_load_lds_dwordx4 v[218:219], off
	v_lshl_add_u64 v[218:219], s[28:29], 0, v[130:131]
	s_mov_b32 m0, s30
	s_nop 0
	global_load_lds_dwordx4 v[218:219], off
	v_lshl_add_u64 v[218:219], s[28:29], 0, v[134:135]
	s_add_i32 m0, s30, 0x2000
	s_nop 0
	global_load_lds_dwordx4 v[218:219], off
	v_lshl_add_u64 v[218:219], v[222:223], 0, s[12:13]
	s_mov_b32 m0, s43
	s_nop 0
	global_load_lds_dwordx4 v[218:219], off
	v_lshl_add_u64 v[218:219], v[224:225], 0, s[12:13]
	s_mov_b32 m0, s44
	s_nop 0
	global_load_lds_dwordx4 v[218:219], off
	s_waitcnt vmcnt(8)
	s_waitcnt lgkmcnt(0)
	s_barrier
	s_waitcnt lgkmcnt(0)
	v_mfma_f32_16x16x32_bf16 v[60:63], v[144:147], v[184:187], v[60:63]
	v_mfma_f32_16x16x32_bf16 v[56:59], v[152:155], v[184:187], v[56:59]
	v_mfma_f32_16x16x32_bf16 v[44:47], v[144:147], v[192:195], v[44:47]
	v_mfma_f32_16x16x32_bf16 v[40:43], v[152:155], v[192:195], v[40:43]
	v_mfma_f32_16x16x32_bf16 v[28:31], v[144:147], v[200:203], v[28:31]
	v_mfma_f32_16x16x32_bf16 v[24:27], v[152:155], v[200:203], v[24:27]
	v_mfma_f32_16x16x32_bf16 v[12:15], v[144:147], v[210:213], v[12:15]
	v_mfma_f32_16x16x32_bf16 v[8:11], v[152:155], v[210:213], v[8:11]
	v_mfma_f32_16x16x32_bf16 v[60:63], v[148:151], v[188:191], v[60:63]
	s_add_i32 s63, s63, 2
	s_add_u32 s26, s26, 0x100
	s_addc_u32 s27, s27, 0
	s_add_u32 s55, s55, 0x100
	s_addc_u32 s62, s62, 0
	s_cmp_gt_u32 s63, 13
	v_mfma_f32_16x16x32_bf16 v[56:59], v[156:159], v[188:191], v[56:59]
	v_mfma_f32_16x16x32_bf16 v[44:47], v[148:151], v[196:199], v[44:47]
	v_mfma_f32_16x16x32_bf16 v[40:43], v[156:159], v[196:199], v[40:43]
	v_mfma_f32_16x16x32_bf16 v[28:31], v[148:151], v[204:207], v[28:31]
	v_mfma_f32_16x16x32_bf16 v[24:27], v[156:159], v[204:207], v[24:27]
	v_mfma_f32_16x16x32_bf16 v[12:15], v[148:151], v[214:217], v[12:15]
	v_mfma_f32_16x16x32_bf16 v[8:11], v[156:159], v[214:217], v[8:11]
	v_mfma_f32_16x16x32_bf16 v[52:55], v[160:163], v[184:187], v[52:55]
	v_mfma_f32_16x16x32_bf16 v[48:51], v[168:171], v[184:187], v[48:51]
	v_mfma_f32_16x16x32_bf16 v[36:39], v[160:163], v[192:195], v[36:39]
	v_mfma_f32_16x16x32_bf16 v[32:35], v[168:171], v[192:195], v[32:35]
	v_mfma_f32_16x16x32_bf16 v[20:23], v[160:163], v[200:203], v[20:23]
	v_mfma_f32_16x16x32_bf16 v[16:19], v[168:171], v[200:203], v[16:19]
	v_mfma_f32_16x16x32_bf16 v[4:7], v[160:163], v[210:213], v[4:7]
	v_mfma_f32_16x16x32_bf16 v[0:3], v[168:171], v[210:213], v[0:3]
	v_mfma_f32_16x16x32_bf16 v[52:55], v[164:167], v[188:191], v[52:55]
	v_mfma_f32_16x16x32_bf16 v[48:51], v[180:183], v[188:191], v[48:51]
	v_mfma_f32_16x16x32_bf16 v[36:39], v[164:167], v[196:199], v[36:39]
	v_mfma_f32_16x16x32_bf16 v[32:35], v[180:183], v[196:199], v[32:35]
	v_mfma_f32_16x16x32_bf16 v[20:23], v[164:167], v[204:207], v[20:23]
	v_mfma_f32_16x16x32_bf16 v[16:19], v[180:183], v[204:207], v[16:19]
	v_mfma_f32_16x16x32_bf16 v[4:7], v[164:167], v[214:217], v[4:7]
	v_mfma_f32_16x16x32_bf16 v[0:3], v[180:183], v[214:217], v[0:3]
	s_barrier
	s_cbranch_scc0 .LBB0_586
	s_setprio 0
	s_and_b64 vcc, exec, s[16:17]
	s_cbranch_vccz .LBB0_589
	s_barrier

.Lp7_wdone:
	s_waitcnt lgkmcnt(0)
	s_barrier
	s_waitcnt lgkmcnt(0)
	v_mfma_f32_16x16x32_bf16 v[92:95], v[88:91], v[160:163], v[92:95]
	v_mfma_f32_16x16x32_bf16 v[20:23], v[120:123], v[160:163], v[20:23]
	v_mfma_f32_16x16x32_bf16 v[84:87], v[88:91], v[168:171], v[84:87]
	v_mfma_f32_16x16x32_bf16 v[12:15], v[120:123], v[168:171], v[12:15]
	v_mfma_f32_16x16x32_bf16 v[76:79], v[88:91], v[192:195], v[76:79]
	v_mfma_f32_16x16x32_bf16 v[4:7], v[120:123], v[192:195], v[4:7]
	v_mfma_f32_16x16x32_bf16 v[40:43], v[88:91], v[218:221], v[40:43]
	v_mfma_f32_16x16x32_bf16 v[24:27], v[120:123], v[218:221], v[24:27]
	v_mfma_f32_16x16x32_bf16 v[92:95], v[96:99], v[164:167], v[92:95]
	s_add_i32 s24, s24, 2
	s_add_u32 s0, s0, 0x100
	s_addc_u32 s1, s1, 0
	s_add_u32 s22, s22, 0x100
	s_addc_u32 s23, s23, 0
	s_cmp_gt_u32 s24, 13
	v_mfma_f32_16x16x32_bf16 v[20:23], v[124:127], v[164:167], v[20:23]
	v_mfma_f32_16x16x32_bf16 v[84:87], v[96:99], v[172:175], v[84:87]
	v_mfma_f32_16x16x32_bf16 v[12:15], v[124:127], v[172:175], v[12:15]
	v_mfma_f32_16x16x32_bf16 v[76:79], v[96:99], v[196:199], v[76:79]
	v_mfma_f32_16x16x32_bf16 v[4:7], v[124:127], v[196:199], v[4:7]
	v_mfma_f32_16x16x32_bf16 v[96:99], v[96:99], v[222:225], v[40:43]
	v_mfma_f32_16x16x32_bf16 v[24:27], v[124:127], v[222:225], v[24:27]
	v_mfma_f32_16x16x32_bf16 v[40:43], v[128:131], v[160:163], v[44:47]
	v_mfma_f32_16x16x32_bf16 v[88:91], v[132:135], v[164:167], v[40:43]
	v_mfma_f32_16x16x32_bf16 v[40:43], v[128:131], v[168:171], v[80:83]
	v_mfma_f32_16x16x32_bf16 v[80:83], v[132:135], v[172:175], v[40:43]
	v_mfma_f32_16x16x32_bf16 v[40:43], v[128:131], v[192:195], v[72:75]
	v_mfma_f32_16x16x32_bf16 v[16:19], v[136:139], v[160:163], v[16:19]
	v_mfma_f32_16x16x32_bf16 v[8:11], v[136:139], v[168:171], v[8:11]
	v_mfma_f32_16x16x32_bf16 v[72:75], v[132:135], v[196:199], v[40:43]
	v_mfma_f32_16x16x32_bf16 v[0:3], v[136:139], v[192:195], v[0:3]
	v_mfma_f32_16x16x32_bf16 v[40:43], v[128:131], v[218:221], v[104:107]
	v_mfma_f32_16x16x32_bf16 v[36:39], v[136:139], v[218:221], v[36:39]
	v_mfma_f32_16x16x32_bf16 v[16:19], v[140:143], v[164:167], v[16:19]
	v_mfma_f32_16x16x32_bf16 v[8:11], v[140:143], v[172:175], v[8:11]
	v_mfma_f32_16x16x32_bf16 v[0:3], v[140:143], v[196:199], v[0:3]
	v_mfma_f32_16x16x32_bf16 v[104:107], v[132:135], v[222:225], v[40:43]
	v_mfma_f32_16x16x32_bf16 v[36:39], v[140:143], v[222:225], v[36:39]
	s_barrier
	s_cbranch_scc0 .LBB0_685
	s_setprio 0
	s_and_b64 vcc, exec, s[38:39]
	s_cbranch_vccz .LBB0_688
	s_barrier

.Lsprio_p11:
.LBB0_806:
	ds_read_b128 v[144:147], v161
	ds_read_b128 v[148:151], v161 offset:1024
	ds_read_b128 v[152:155], v161 offset:2048
	ds_read_b128 v[164:167], v161 offset:3072
	ds_read_b128 v[168:171], v162
	ds_read_b128 v[172:175], v162 offset:1024
	ds_read_b128 v[176:179], v162 offset:2048
	ds_read_b128 v[180:183], v162 offset:3072
	s_add_u32 s28, s26, 0xfff50080
	s_addc_u32 s29, s27, -1
	s_cmp_eq_u32 s55, 40
	s_cselect_b32 s35, s5, s29
	s_cselect_b32 s34, s4, s28
	s_cselect_b32 s29, s25, s54
	s_cselect_b32 s28, s24, s53
	v_lshl_add_u64 v[156:157], s[26:27], 0, v[136:137]
	s_add_i32 m0, s37, 0xc000
	ds_read_b128 v[184:187], v163
	ds_read_b128 v[188:191], v163 offset:1024
	ds_read_b128 v[192:195], v163 offset:2048
	ds_read_b128 v[196:199], v163 offset:3072
	ds_read_b128 v[200:203], v163 offset:4096
	ds_read_b128 v[204:207], v163 offset:5120
	ds_read_b128 v[208:211], v163 offset:6144
	ds_read_b128 v[212:215], v163 offset:7168
	global_load_lds_dwordx4 v[156:157], off
	v_lshl_add_u64 v[156:157], s[26:27], 0, v[138:139]
	s_add_i32 m0, s37, 0xe000
	s_nop 0
	global_load_lds_dwordx4 v[156:157], off
	s_waitcnt vmcnt(8)
	s_waitcnt lgkmcnt(0)
	s_barrier
	s_waitcnt lgkmcnt(0)
	v_mfma_f32_16x16x32_bf16 v[124:127], v[144:147], v[184:187], v[124:127]
	v_mfma_f32_16x16x32_bf16 v[120:123], v[152:155], v[184:187], v[120:123]
	v_mfma_f32_16x16x32_bf16 v[108:111], v[144:147], v[192:195], v[108:111]
	v_mfma_f32_16x16x32_bf16 v[104:107], v[152:155], v[192:195], v[104:107]
	v_mfma_f32_16x16x32_bf16 v[92:95], v[144:147], v[200:203], v[92:95]
	v_mfma_f32_16x16x32_bf16 v[88:91], v[152:155], v[200:203], v[88:91]
	v_mfma_f32_16x16x32_bf16 v[76:79], v[144:147], v[208:211], v[76:79]
	v_mfma_f32_16x16x32_bf16 v[72:75], v[152:155], v[208:211], v[72:75]
	v_mfma_f32_16x16x32_bf16 v[124:127], v[148:151], v[188:191], v[124:127]
	v_mfma_f32_16x16x32_bf16 v[120:123], v[164:167], v[188:191], v[120:123]
	v_mfma_f32_16x16x32_bf16 v[108:111], v[148:151], v[196:199], v[108:111]
	v_mfma_f32_16x16x32_bf16 v[104:107], v[164:167], v[196:199], v[104:107]
	v_mfma_f32_16x16x32_bf16 v[92:95], v[148:151], v[204:207], v[92:95]
	v_mfma_f32_16x16x32_bf16 v[88:91], v[164:167], v[204:207], v[88:91]
	v_mfma_f32_16x16x32_bf16 v[76:79], v[148:151], v[212:215], v[76:79]
	v_mfma_f32_16x16x32_bf16 v[72:75], v[164:167], v[212:215], v[72:75]
	v_mfma_f32_16x16x32_bf16 v[116:119], v[168:171], v[184:187], v[116:119]
	v_mfma_f32_16x16x32_bf16 v[112:115], v[176:179], v[184:187], v[112:115]
	v_mfma_f32_16x16x32_bf16 v[100:103], v[168:171], v[192:195], v[100:103]
	v_mfma_f32_16x16x32_bf16 v[96:99], v[176:179], v[192:195], v[96:99]
	v_mfma_f32_16x16x32_bf16 v[84:87], v[168:171], v[200:203], v[84:87]
	v_mfma_f32_16x16x32_bf16 v[80:83], v[176:179], v[200:203], v[80:83]
	v_mfma_f32_16x16x32_bf16 v[68:71], v[168:171], v[208:211], v[68:71]
	v_mfma_f32_16x16x32_bf16 v[64:67], v[176:179], v[208:211], v[64:67]
	v_mfma_f32_16x16x32_bf16 v[116:119], v[172:175], v[188:191], v[116:119]
	v_mfma_f32_16x16x32_bf16 v[112:115], v[180:183], v[188:191], v[112:115]
	v_mfma_f32_16x16x32_bf16 v[100:103], v[172:175], v[196:199], v[100:103]
	v_mfma_f32_16x16x32_bf16 v[96:99], v[180:183], v[196:199], v[96:99]
	v_mfma_f32_16x16x32_bf16 v[84:87], v[172:175], v[204:207], v[84:87]
	v_mfma_f32_16x16x32_bf16 v[80:83], v[180:183], v[204:207], v[80:83]
	v_mfma_f32_16x16x32_bf16 v[68:71], v[172:175], v[212:215], v[68:71]
	v_mfma_f32_16x16x32_bf16 v[64:67], v[180:183], v[212:215], v[64:67]
	s_barrier
	s_add_i32 s56, s47, s36
	v_lshl_add_u64 v[156:157], s[28:29], 0, v[130:131]
	s_mov_b32 m0, s56
	ds_read_b128 v[184:187], v163 offset:16384
	ds_read_b128 v[188:191], v163 offset:17408
	ds_read_b128 v[192:195], v163 offset:18432
	ds_read_b128 v[196:199], v163 offset:19456
	ds_read_b128 v[200:203], v163 offset:20480
	ds_read_b128 v[204:207], v163 offset:21504
	ds_read_b128 v[208:211], v163 offset:22528
	ds_read_b128 v[212:215], v163 offset:23552
	global_load_lds_dwordx4 v[156:157], off
	s_add_i32 m0, s56, 0x2000
	s_add_u32 s56, s28, 0xb0000
	v_lshl_add_u64 v[216:217], s[28:29], 0, v[134:135]
	s_addc_u32 s57, s29, 0
	s_add_i32 s58, s48, s36
	global_load_lds_dwordx4 v[216:217], off
	v_lshl_add_u64 v[218:219], s[56:57], 0, v[130:131]
	s_mov_b32 m0, s58
	v_lshl_add_u64 v[220:221], s[34:35], 0, v[132:133]
	global_load_lds_dwordx4 v[218:219], off
	v_lshl_add_u64 v[218:219], s[56:57], 0, v[134:135]
	s_add_i32 m0, s58, 0x2000
	s_nop 0
	global_load_lds_dwordx4 v[218:219], off
	v_lshl_add_u64 v[218:219], s[34:35], 0, v[128:129]
	s_mov_b32 m0, s37
	s_nop 0
	global_load_lds_dwordx4 v[218:219], off
	s_mov_b32 m0, s38
	s_nop 0
	global_load_lds_dwordx4 v[220:221], off
	s_waitcnt vmcnt(8)
	s_waitcnt lgkmcnt(0)
	s_barrier
	s_waitcnt lgkmcnt(0)
	v_mfma_f32_16x16x32_bf16 v[60:63], v[144:147], v[184:187], v[60:63]
	v_mfma_f32_16x16x32_bf16 v[56:59], v[152:155], v[184:187], v[56:59]
	v_mfma_f32_16x16x32_bf16 v[44:47], v[144:147], v[192:195], v[44:47]
	v_mfma_f32_16x16x32_bf16 v[40:43], v[152:155], v[192:195], v[40:43]
	v_mfma_f32_16x16x32_bf16 v[28:31], v[144:147], v[200:203], v[28:31]
	v_mfma_f32_16x16x32_bf16 v[24:27], v[152:155], v[200:203], v[24:27]
	v_mfma_f32_16x16x32_bf16 v[12:15], v[144:147], v[208:211], v[12:15]
	v_mfma_f32_16x16x32_bf16 v[8:11], v[152:155], v[208:211], v[8:11]
	v_mfma_f32_16x16x32_bf16 v[60:63], v[148:151], v[188:191], v[60:63]
	v_mfma_f32_16x16x32_bf16 v[56:59], v[164:167], v[188:191], v[56:59]
	v_mfma_f32_16x16x32_bf16 v[44:47], v[148:151], v[196:199], v[44:47]
	v_mfma_f32_16x16x32_bf16 v[40:43], v[164:167], v[196:199], v[40:43]
	v_mfma_f32_16x16x32_bf16 v[28:31], v[148:151], v[204:207], v[28:31]
	v_mfma_f32_16x16x32_bf16 v[24:27], v[164:167], v[204:207], v[24:27]
	v_mfma_f32_16x16x32_bf16 v[12:15], v[148:151], v[212:215], v[12:15]
	v_mfma_f32_16x16x32_bf16 v[8:11], v[164:167], v[212:215], v[8:11]
	v_mfma_f32_16x16x32_bf16 v[52:55], v[168:171], v[184:187], v[52:55]
	v_mfma_f32_16x16x32_bf16 v[48:51], v[176:179], v[184:187], v[48:51]
	v_mfma_f32_16x16x32_bf16 v[36:39], v[168:171], v[192:195], v[36:39]
	v_mfma_f32_16x16x32_bf16 v[32:35], v[176:179], v[192:195], v[32:35]
	v_mfma_f32_16x16x32_bf16 v[20:23], v[168:171], v[200:203], v[20:23]
	v_mfma_f32_16x16x32_bf16 v[16:19], v[176:179], v[200:203], v[16:19]
	v_mfma_f32_16x16x32_bf16 v[4:7], v[168:171], v[208:211], v[4:7]
	v_mfma_f32_16x16x32_bf16 v[0:3], v[176:179], v[208:211], v[0:3]
	v_mfma_f32_16x16x32_bf16 v[52:55], v[172:175], v[188:191], v[52:55]
	v_mfma_f32_16x16x32_bf16 v[48:51], v[180:183], v[188:191], v[48:51]
	v_mfma_f32_16x16x32_bf16 v[36:39], v[172:175], v[196:199], v[36:39]
	v_mfma_f32_16x16x32_bf16 v[32:35], v[180:183], v[196:199], v[32:35]
	v_mfma_f32_16x16x32_bf16 v[20:23], v[172:175], v[204:207], v[20:23]
	v_mfma_f32_16x16x32_bf16 v[16:19], v[180:183], v[204:207], v[16:19]
	v_mfma_f32_16x16x32_bf16 v[4:7], v[172:175], v[212:215], v[4:7]
	v_mfma_f32_16x16x32_bf16 v[0:3], v[180:183], v[212:215], v[0:3]
	s_barrier
	s_add_i32 s56, 0, 0x18000
	s_add_i32 s57, 0, 0x1c000
	v_add_u32_e32 v164, s56, v159
	v_add_u32_e32 v180, s57, v159
	ds_read_b128 v[144:147], v164
	ds_read_b128 v[148:151], v164 offset:1024
	ds_read_b128 v[152:155], v164 offset:2048
	ds_read_b128 v[164:167], v164 offset:3072
	ds_read_b128 v[168:171], v180
	ds_read_b128 v[172:175], v180 offset:1024
	ds_read_b128 v[176:179], v180 offset:2048
	ds_read_b128 v[180:183], v180 offset:3072
	s_add_u32 s34, s34, 0xb0000
	s_addc_u32 s35, s35, 0
	s_mov_b32 m0, s39
	v_lshl_add_u64 v[222:223], s[34:35], 0, v[128:129]
	ds_read_b128 v[184:187], v163 offset:32768
	ds_read_b128 v[188:191], v163 offset:33792
	ds_read_b128 v[192:195], v163 offset:34816
	ds_read_b128 v[196:199], v163 offset:35840
	ds_read_b128 v[200:203], v163 offset:36864
	ds_read_b128 v[204:207], v163 offset:37888
	ds_read_b128 v[208:211], v163 offset:38912
	ds_read_b128 v[212:215], v163 offset:39936
	global_load_lds_dwordx4 v[222:223], off
	v_lshl_add_u64 v[222:223], s[34:35], 0, v[132:133]
	s_mov_b32 m0, s40
	s_nop 0
	global_load_lds_dwordx4 v[222:223], off
	s_waitcnt vmcnt(8)
	s_waitcnt lgkmcnt(0)
	s_barrier
	s_waitcnt lgkmcnt(0)
	v_mfma_f32_16x16x32_bf16 v[124:127], v[144:147], v[184:187], v[124:127]
	v_mfma_f32_16x16x32_bf16 v[120:123], v[152:155], v[184:187], v[120:123]
	v_mfma_f32_16x16x32_bf16 v[108:111], v[144:147], v[192:195], v[108:111]
	v_mfma_f32_16x16x32_bf16 v[104:107], v[152:155], v[192:195], v[104:107]
	v_mfma_f32_16x16x32_bf16 v[92:95], v[144:147], v[200:203], v[92:95]
	v_mfma_f32_16x16x32_bf16 v[88:91], v[152:155], v[200:203], v[88:91]
	v_mfma_f32_16x16x32_bf16 v[76:79], v[144:147], v[208:211], v[76:79]
	v_mfma_f32_16x16x32_bf16 v[72:75], v[152:155], v[208:211], v[72:75]
	v_mfma_f32_16x16x32_bf16 v[124:127], v[148:151], v[188:191], v[124:127]
	v_mfma_f32_16x16x32_bf16 v[120:123], v[164:167], v[188:191], v[120:123]
	v_mfma_f32_16x16x32_bf16 v[108:111], v[148:151], v[196:199], v[108:111]
	v_mfma_f32_16x16x32_bf16 v[104:107], v[164:167], v[196:199], v[104:107]
	v_mfma_f32_16x16x32_bf16 v[92:95], v[148:151], v[204:207], v[92:95]
	v_mfma_f32_16x16x32_bf16 v[88:91], v[164:167], v[204:207], v[88:91]
	v_mfma_f32_16x16x32_bf16 v[76:79], v[148:151], v[212:215], v[76:79]
	v_mfma_f32_16x16x32_bf16 v[72:75], v[164:167], v[212:215], v[72:75]
	v_mfma_f32_16x16x32_bf16 v[116:119], v[168:171], v[184:187], v[116:119]
	v_mfma_f32_16x16x32_bf16 v[112:115], v[176:179], v[184:187], v[112:115]
	v_mfma_f32_16x16x32_bf16 v[100:103], v[168:171], v[192:195], v[100:103]
	v_mfma_f32_16x16x32_bf16 v[96:99], v[176:179], v[192:195], v[96:99]
	v_mfma_f32_16x16x32_bf16 v[84:87], v[168:171], v[200:203], v[84:87]
	v_mfma_f32_16x16x32_bf16 v[80:83], v[176:179], v[200:203], v[80:83]
	v_mfma_f32_16x16x32_bf16 v[68:71], v[168:171], v[208:211], v[68:71]
	v_mfma_f32_16x16x32_bf16 v[64:67], v[176:179], v[208:211], v[64:67]
	v_mfma_f32_16x16x32_bf16 v[116:119], v[172:175], v[188:191], v[116:119]
	v_mfma_f32_16x16x32_bf16 v[112:115], v[180:183], v[188:191], v[112:115]
	v_mfma_f32_16x16x32_bf16 v[100:103], v[172:175], v[196:199], v[100:103]
	v_mfma_f32_16x16x32_bf16 v[96:99], v[180:183], v[196:199], v[96:99]
	v_mfma_f32_16x16x32_bf16 v[84:87], v[172:175], v[204:207], v[84:87]
	v_mfma_f32_16x16x32_bf16 v[80:83], v[180:183], v[204:207], v[80:83]
	v_mfma_f32_16x16x32_bf16 v[68:71], v[172:175], v[212:215], v[68:71]
	v_mfma_f32_16x16x32_bf16 v[64:67], v[180:183], v[212:215], v[64:67]
	s_barrier
	s_add_i32 s34, s56, s36
	v_lshl_add_u64 v[156:157], v[156:157], 0, s[10:11]
	s_mov_b32 m0, s34
	ds_read_b128 v[184:187], v163 offset:49152
	ds_read_b128 v[188:191], v163 offset:50176
	ds_read_b128 v[192:195], v163 offset:51200
	ds_read_b128 v[196:199], v163 offset:52224
	ds_read_b128 v[200:203], v163 offset:53248
	ds_read_b128 v[204:207], v163 offset:54272
	ds_read_b128 v[208:211], v163 offset:55296
	ds_read_b128 v[212:215], v163 offset:56320
	global_load_lds_dwordx4 v[156:157], off
	s_add_i32 m0, s34, 0x2000
	s_add_u32 s28, s28, 0xb0080
	v_lshl_add_u64 v[156:157], v[216:217], 0, s[10:11]
	s_addc_u32 s29, s29, 0
	s_add_i32 s34, s57, s36
	global_load_lds_dwordx4 v[156:157], off
	v_lshl_add_u64 v[156:157], s[28:29], 0, v[130:131]
	s_mov_b32 m0, s34
	s_nop 0
	global_load_lds_dwordx4 v[156:157], off
	v_lshl_add_u64 v[156:157], s[28:29], 0, v[134:135]
	s_add_i32 m0, s34, 0x2000
	s_nop 0
	global_load_lds_dwordx4 v[156:157], off
	v_lshl_add_u64 v[156:157], v[218:219], 0, s[10:11]
	s_mov_b32 m0, s44
	s_nop 0
	global_load_lds_dwordx4 v[156:157], off
	v_lshl_add_u64 v[156:157], v[220:221], 0, s[10:11]
	s_mov_b32 m0, s45
	s_nop 0
	global_load_lds_dwordx4 v[156:157], off
	s_waitcnt vmcnt(8)
	s_waitcnt lgkmcnt(0)
	s_barrier
	s_waitcnt lgkmcnt(0)
	v_mfma_f32_16x16x32_bf16 v[60:63], v[144:147], v[184:187], v[60:63]
	v_mfma_f32_16x16x32_bf16 v[56:59], v[152:155], v[184:187], v[56:59]
	v_mfma_f32_16x16x32_bf16 v[44:47], v[144:147], v[192:195], v[44:47]
	v_mfma_f32_16x16x32_bf16 v[40:43], v[152:155], v[192:195], v[40:43]
	v_mfma_f32_16x16x32_bf16 v[28:31], v[144:147], v[200:203], v[28:31]
	v_mfma_f32_16x16x32_bf16 v[24:27], v[152:155], v[200:203], v[24:27]
	v_mfma_f32_16x16x32_bf16 v[12:15], v[144:147], v[208:211], v[12:15]
	v_mfma_f32_16x16x32_bf16 v[8:11], v[152:155], v[208:211], v[8:11]
	v_mfma_f32_16x16x32_bf16 v[60:63], v[148:151], v[188:191], v[60:63]
	s_add_i32 s55, s55, 2
	s_add_u32 s26, s26, 0x100
	s_addc_u32 s27, s27, 0
	s_add_u32 s53, s53, 0x100
	s_addc_u32 s54, s54, 0
	s_cmp_gt_u32 s55, 41
	v_mfma_f32_16x16x32_bf16 v[56:59], v[164:167], v[188:191], v[56:59]
	v_mfma_f32_16x16x32_bf16 v[44:47], v[148:151], v[196:199], v[44:47]
	v_mfma_f32_16x16x32_bf16 v[40:43], v[164:167], v[196:199], v[40:43]
	v_mfma_f32_16x16x32_bf16 v[28:31], v[148:151], v[204:207], v[28:31]
	v_mfma_f32_16x16x32_bf16 v[24:27], v[164:167], v[204:207], v[24:27]
	v_mfma_f32_16x16x32_bf16 v[12:15], v[148:151], v[212:215], v[12:15]
	v_mfma_f32_16x16x32_bf16 v[8:11], v[164:167], v[212:215], v[8:11]
	v_mfma_f32_16x16x32_bf16 v[52:55], v[168:171], v[184:187], v[52:55]
	v_mfma_f32_16x16x32_bf16 v[48:51], v[176:179], v[184:187], v[48:51]
	v_mfma_f32_16x16x32_bf16 v[36:39], v[168:171], v[192:195], v[36:39]
	v_mfma_f32_16x16x32_bf16 v[32:35], v[176:179], v[192:195], v[32:35]
	v_mfma_f32_16x16x32_bf16 v[20:23], v[168:171], v[200:203], v[20:23]
	v_mfma_f32_16x16x32_bf16 v[16:19], v[176:179], v[200:203], v[16:19]
	v_mfma_f32_16x16x32_bf16 v[4:7], v[168:171], v[208:211], v[4:7]
	v_mfma_f32_16x16x32_bf16 v[0:3], v[176:179], v[208:211], v[0:3]
	v_mfma_f32_16x16x32_bf16 v[52:55], v[172:175], v[188:191], v[52:55]
	v_mfma_f32_16x16x32_bf16 v[48:51], v[180:183], v[188:191], v[48:51]
	v_mfma_f32_16x16x32_bf16 v[36:39], v[172:175], v[196:199], v[36:39]
	v_mfma_f32_16x16x32_bf16 v[32:35], v[180:183], v[196:199], v[32:35]
	v_mfma_f32_16x16x32_bf16 v[20:23], v[172:175], v[204:207], v[20:23]
	v_mfma_f32_16x16x32_bf16 v[16:19], v[180:183], v[204:207], v[16:19]
	v_mfma_f32_16x16x32_bf16 v[4:7], v[172:175], v[212:215], v[4:7]
	v_mfma_f32_16x16x32_bf16 v[0:3], v[180:183], v[212:215], v[0:3]
	s_barrier
	s_cbranch_scc0 .LBB0_806
	s_setprio 0
	s_and_b64 vcc, exec, s[12:13]
	s_cbranch_vccz .LBB0_809
	s_barrier
